# NSA_IN layer-3 weight conversion moved from the HGRN2 phase spare workgroups into the HG_IN GEMM unit boundaries (LDS-free 2col x 8k per lane), on top of v24
# baseline (speedup 1.0000x reference)
;     __device__ __forceinline__ bool next(int i, pg8::Unit& u) const { if (i >= 2) return false; u.pm = 8 * (j >> 5) + 2 * i + ((j >> 4) & 1); u.pn = j & 15; return true; }
;     __device__ __forceinline__ bool next(int i, pg8::Unit& u) const { if (i >= 1) return false; const int x = c & 7, l = c >> 3; u.pm = 8 * (x >> 1) + 4 + (l & 3); u.pn = 8 * (x & 1) + (l >> 2); return true; }
;     __device__ __forceinline__ bool next(int i, pg8::Unit& u) const { if (i >= 2) return false; u.pm = e >> 2; u.pn = 4 * i + (e & 3); return true; }
;     __host__ __device__ bool next(int i, Unit& u) const {
;         const long L = (long)i * G + c; if (L >= nwg) return false;
;         int wgid = (int)L; { const int q = nwg / NXCD, r = nwg % NXCD, xcd = wgid % NXCD, off = wgid / NXCD; wgid = (xcd < r ? xcd * (q + 1) : r * (q + 1) + (xcd - r) * q) + off; }
;         const int nig = WGM * nN, gid = wgid / nig, fm = gid * WGM, gsz = (nM - fm) < WGM ? (nM - fm) : WGM;
;         u.pm = fm + ((wgid % nig) % gsz); u.pn = (wgid % nig) / gsz; return true;
.LBB0_1488:
	v_readlane_b32 s4, v254, 0
	s_cmp_lt_i32 s4, 13
	s_cselect_b64 s[0:1], -1, 0
	s_and_b64 s[2:3], s[0:1], s[2:3]
	s_andn2_b64 vcc, exec, s[2:3]
	v_readlane_b32 s5, v254, 1
	v_readlane_b32 s6, v254, 2
	v_readlane_b32 s7, v254, 3
	s_cbranch_vccnz .LBB0_1513
	v_readlane_b32 s2, v254, 7
	v_readlane_b32 s3, v254, 8
	s_cmpk_gt_i32 s85, 0x7ff
	v_writelane_b32 v254, s2, 7
	v_readfirstlane_b32 s12, v0
	s_nop 0
	v_writelane_b32 v254, s3, 8
	s_cbranch_scc1 .LBB0_1513
	s_mov_b32 s98, 0
	s_ashr_i32 s33, s85, 31
	s_lshr_b32 s2, s33, 29
	s_add_i32 s5, s85, s2
	s_and_b32 s2, s5, -8
	s_sub_i32 s6, s85, s2
	s_cmp_gt_i32 s6, -1
	s_cbranch_scc0 .LBB0_1492
	s_lshl_b32 s4, s6, 8
	s_cbranch_execz .LBB0_1493
	s_branch .LBB0_1494

;     __device__ __forceinline__ void operator()(const f32x4 (&acc)[2][2][4][2], const Unit& u, int wr, int wc, int fr, int fq) const {
;         const int row0 = u.pm * BM + wr * 64 + fr, col0 = u.pn * BM + wc * 32 + 8 * fq;
;         float scv[2][4];
; #pragma unroll
;         for (int ai = 0; ai < 2; ++ai)
; #pragma unroll
;             for (int m = 0; m < 4; ++m) scv[ai][m] = rs[row0 + ai * HALF + m * 16];
; #pragma unroll
;         for (int ai = 0; ai < 2; ++ai)
; #pragma unroll
;             for (int m = 0; m < 4; ++m) { const int row = row0 + ai * HALF + m * 16; const float sc = scv[ai][m]; bf16_t* rowp = O + (size_t)row * ldc + col0;
.LBB0_1509:
	v_lshl_add_u32 v148, s30, 8, v1
	v_ashrrev_i32_e32 v149, 31, v148
	v_or_b32_e32 v160, 16, v148
	v_or_b32_e32 v164, 32, v148
	v_lshl_add_u64 v[156:157], v[148:149], 2, s[8:9]
	v_ashrrev_i32_e32 v161, 31, v160
	v_ashrrev_i32_e32 v165, 31, v164
	global_load_dword v158, v[156:157], off
	v_lshl_add_u64 v[162:163], v[160:161], 2, s[8:9]
	v_lshl_add_u64 v[166:167], v[164:165], 2, s[8:9]
	global_load_dword v162, v[162:163], off
	v_or_b32_e32 v168, 48, v148
	global_load_dword v166, v[166:167], off
	v_ashrrev_i32_e32 v169, 31, v168
	v_lshl_add_u64 v[170:171], v[168:169], 2, s[8:9]
	global_load_dword v150, v[170:171], off
	global_load_dword v172, v[156:157], off offset:512
	global_load_dword v174, v[156:157], off offset:576
	global_load_dword v152, v[156:157], off offset:640
	global_load_dword v146, v[156:157], off offset:704
	v_lshl_or_b32 v170, s58, 8, v151
	v_ashrrev_i32_e32 v171, 31, v170
	v_lshlrev_b64 v[148:149], 15, v[148:149]
	v_lshlrev_b64 v[170:171], 1, v[170:171]
	v_lshl_add_u64 v[148:149], s[6:7], 0, v[148:149]
	v_lshlrev_b64 v[160:161], 15, v[160:161]
	v_lshlrev_b64 v[164:165], 15, v[164:165]
	v_lshlrev_b64 v[168:169], 15, v[168:169]
	v_lshl_add_u64 v[148:149], v[148:149], 0, v[170:171]
	v_lshl_add_u64 v[156:157], s[6:7], 0, v[160:161]
	v_lshl_add_u64 v[160:161], s[6:7], 0, v[164:165]
	v_lshl_add_u64 v[164:165], s[6:7], 0, v[168:169]
	v_lshl_add_u64 v[156:157], v[156:157], 0, v[170:171]
	v_lshl_add_u64 v[160:161], v[160:161], 0, v[170:171]
	v_lshl_add_u64 v[164:165], v[164:165], 0, v[170:171]
	s_waitcnt vmcnt(0)
	s_lshl_b32 s101, s98, 11
	s_lshl_b32 s77, s85, 3
	s_add_i32 s101, s101, s77
	s_add_i32 s101, s101, s90
	s_mov_b32 s82, 0
	s_cmp_ge_u32 s101, 0x3c00
	s_cbranch_scc1 .Lcv_p1_done
	s_mul_hi_u32 s77, s101, 0x88888889
	s_lshr_b32 s77, s77, 6
	s_mul_i32 vcc_lo, s77, 0x78
	s_sub_i32 s101, s101, vcc_lo
	v_readlane_b32 s80, v254, 7
	v_readlane_b32 s81, v254, 8
	s_nop 4
	s_load_dwordx2 s[72:73], s[80:81], 0x18
	s_load_dwordx2 s[80:81], s[80:81], 0x8
	s_mul_i32 vcc_lo, s77, 0x163000
	s_lshl_b32 vcc_hi, s77, 7
	s_add_i32 vcc_hi, vcc_hi, 0xc000
	s_lshl_b32 s77, s77, 6
	s_add_u32 s92, s70, 0x5c00000
	s_addc_u32 s93, s71, 0
	s_add_u32 s92, s92, s77
	s_addc_u32 s93, s93, 0
	s_mul_i32 s77, s101, 3
	s_waitcnt lgkmcnt(0)
	s_add_u32 s72, s72, 0xb180000
	s_addc_u32 s73, s73, 0
	s_add_u32 s72, s72, vcc_lo
	s_addc_u32 s73, s73, 0
	s_add_u32 s80, s80, vcc_hi
	s_addc_u32 s81, s81, 0
	s_add_i32 vcc_lo, s77, 1
	s_cmp_ge_u32 vcc_lo, 0x163
	s_cbranch_scc1 .Lcvp_1
	s_lshl_b32 s101, vcc_lo, 7
	s_cmp_lt_u32 vcc_lo, 0xe0
	s_cbranch_scc1 .Lcvs_1
	s_addk_i32 s101, 0x180
	s_cmp_lt_u32 vcc_lo, 0x160
	s_cbranch_scc1 .Lcvs_1
	s_addk_i32 s101, 0xbe80
.Lcvs_1:
	s_add_u32 s74, s72, s101
	s_addc_u32 s75, s73, 0
	s_or_b32 s82, s82, 4
	s_branch .Lcvd_1
.Lcvp_1:
	s_or_b32 s82, s82, 8
.Lcvd_1:
	s_lshl_b32 s101, vcc_lo, 18
	s_add_u32 s94, s92, s101
	s_addc_u32 s95, s93, 0
	s_add_i32 vcc_lo, s77, 2
	s_cmp_ge_u32 vcc_lo, 0x163
	s_cbranch_scc1 .Lcvp_2
	s_lshl_b32 s101, vcc_lo, 7
	s_cmp_lt_u32 vcc_lo, 0xe0
	s_cbranch_scc1 .Lcvs_2
	s_addk_i32 s101, 0x180
	s_cmp_lt_u32 vcc_lo, 0x160
	s_cbranch_scc1 .Lcvs_2
	s_addk_i32 s101, 0xbe80
.Lcvs_2:
	s_add_u32 s88, s72, s101
	s_addc_u32 s89, s73, 0
	s_or_b32 s82, s82, 16
	s_branch .Lcvd_2
.Lcvp_2:
	s_or_b32 s82, s82, 32
.Lcvd_2:
	s_lshl_b32 s101, vcc_lo, 18
	s_add_u32 s96, s92, s101
	s_addc_u32 s97, s93, 0
	s_add_i32 vcc_lo, s77, 0
	s_cmp_ge_u32 vcc_lo, 0x163
	s_cbranch_scc1 .Lcvp_0
	s_lshl_b32 s101, vcc_lo, 7
	s_cmp_lt_u32 vcc_lo, 0xe0
	s_cbranch_scc1 .Lcvs_0
	s_addk_i32 s101, 0x180
	s_cmp_lt_u32 vcc_lo, 0x160
	s_cbranch_scc1 .Lcvs_0
	s_addk_i32 s101, 0xbe80
.Lcvs_0:
	s_add_u32 s72, s72, s101
	s_addc_u32 s73, s73, 0
	s_or_b32 s82, s82, 1
	s_branch .Lcvd_0
.Lcvp_0:
	s_or_b32 s82, s82, 2
.Lcvd_0:
	s_lshl_b32 s101, vcc_lo, 18
	s_add_u32 s92, s92, s101
	s_addc_u32 s93, s93, 0
	v_and_b32_e32 v208, 63, v216
	v_lshrrev_b32_e32 v209, 4, v208
	v_and_b32_e32 v210, 15, v208
	v_mul_u32_u24_e32 v211, 0x58c00, v209
	v_lshl_add_u32 v211, v210, 3, v211
	v_lshlrev_b32_e32 v212, 5, v209
	v_lshlrev_b32_e32 v213, 14, v210
	v_lshl_add_u32 v213, v209, 4, v213
	v_add_u32_e32 v218, 0x2000, v213
	global_load_dwordx4 v[222:225], v212, s[80:81]
	global_load_dwordx4 v[226:229], v212, s[80:81] offset:16
	s_bfe_u32 vcc_lo, s82, 0x20000
	s_cmp_eq_u32 vcc_lo, 1
	s_cbranch_scc0 .Lcvl_0
	v_mov_b32_e32 v219, v211
	global_load_dwordx2 v[176:177], v219, s[72:73] nt
	v_add_u32_e32 v219, 0xb180, v219
	global_load_dwordx2 v[178:179], v219, s[72:73] nt
	v_add_u32_e32 v219, 0xb180, v219
	global_load_dwordx2 v[180:181], v219, s[72:73] nt
	v_add_u32_e32 v219, 0xb180, v219
	global_load_dwordx2 v[182:183], v219, s[72:73] nt
	v_add_u32_e32 v219, 0xb180, v219
	global_load_dwordx2 v[184:185], v219, s[72:73] nt
	v_add_u32_e32 v219, 0xb180, v219
	global_load_dwordx2 v[186:187], v219, s[72:73] nt
	v_add_u32_e32 v219, 0xb180, v219
	global_load_dwordx2 v[188:189], v219, s[72:73] nt
	v_add_u32_e32 v219, 0xb180, v219
	global_load_dwordx2 v[190:191], v219, s[72:73] nt
.Lcvl_0:
	s_bfe_u32 vcc_lo, s82, 0x20002
	s_cmp_eq_u32 vcc_lo, 1
	s_cbranch_scc0 .Lcvl_1
	v_mov_b32_e32 v219, v211
	global_load_dwordx2 v[192:193], v219, s[74:75] nt
	v_add_u32_e32 v219, 0xb180, v219
	global_load_dwordx2 v[194:195], v219, s[74:75] nt
	v_add_u32_e32 v219, 0xb180, v219
	global_load_dwordx2 v[196:197], v219, s[74:75] nt
	v_add_u32_e32 v219, 0xb180, v219
	global_load_dwordx2 v[198:199], v219, s[74:75] nt
	v_add_u32_e32 v219, 0xb180, v219
	global_load_dwordx2 v[200:201], v219, s[74:75] nt
	v_add_u32_e32 v219, 0xb180, v219
	global_load_dwordx2 v[202:203], v219, s[74:75] nt
	v_add_u32_e32 v219, 0xb180, v219
	global_load_dwordx2 v[204:205], v219, s[74:75] nt
	v_add_u32_e32 v219, 0xb180, v219
	global_load_dwordx2 v[206:207], v219, s[74:75] nt
; __device__ __forceinline__ unsigned cvt_pk_bf16(float lo, float hi) { unsigned r; asm volatile("v_cvt_pk_bf16_f32 %0, %1, %2" : "=v"(r) : "v"(lo), "v"(hi)); return r; }
;     __device__ __forceinline__ void operator()(const f32x4 (&acc)[2][2][4][2], const Unit& u, int wr, int wc, int fr, int fq) const {
;     ...
;             for (int m = 0; m < 4; ++m) { const int row = row0 + ai * HALF + m * 16; const float sc = scv[ai][m]; bf16_t* rowp = O + (size_t)row * ldc + col0;
; #pragma unroll
;                 for (int bj = 0; bj < 2; ++bj) { const f32x4 v0 = acc[ai][bj][m][0] * sc, v1 = acc[ai][bj][m][1] * sc;
;                     u32x4 w; w.x = cvt_pk_bf16(v0[0], v0[1]); w.y = cvt_pk_bf16(v0[2], v0[3]); w.z = cvt_pk_bf16(v1[0], v1[1]); w.w = cvt_pk_bf16(v1[2], v1[3]);
;                     *(u32x4*)(rowp + bj * HALF) = w; } }
.Lcvl_1:
	s_bfe_u32 vcc_lo, s82, 0x20004
	s_cmp_eq_u32 vcc_lo, 1
	s_cbranch_scc0 .Lcvl_2
	v_mov_b32_e32 v219, v211
	global_load_dwordx2 v[230:231], v219, s[88:89] nt
	v_add_u32_e32 v219, 0xb180, v219
	global_load_dwordx2 v[232:233], v219, s[88:89] nt
	v_add_u32_e32 v219, 0xb180, v219
	global_load_dwordx2 v[234:235], v219, s[88:89] nt
	v_add_u32_e32 v219, 0xb180, v219
	global_load_dwordx2 v[236:237], v219, s[88:89] nt
	v_add_u32_e32 v219, 0xb180, v219
	global_load_dwordx2 v[238:239], v219, s[88:89] nt
	v_add_u32_e32 v219, 0xb180, v219
	global_load_dwordx2 v[240:241], v219, s[88:89] nt
	v_add_u32_e32 v219, 0xb180, v219
	global_load_dwordx2 v[242:243], v219, s[88:89] nt
	v_add_u32_e32 v219, 0xb180, v219
	global_load_dwordx2 v[244:245], v219, s[88:89] nt
.Lcvl_2:
.Lcv_p1_done:
	v_pk_mul_f32 v[124:125], v[124:125], v[158:159] op_sel_hi:[1,0]
	v_pk_mul_f32 v[128:129], v[128:129], v[158:159] op_sel_hi:[1,0]
	v_pk_mul_f32 v[126:127], v[126:127], v[158:159] op_sel_hi:[1,0]
	v_pk_mul_f32 v[122:123], v[122:123], v[158:159] op_sel_hi:[1,0]
	v_pk_mul_f32 v[108:109], v[108:109], v[158:159] op_sel_hi:[1,0]
	v_pk_mul_f32 v[106:107], v[106:107], v[158:159] op_sel_hi:[1,0]
	v_pk_mul_f32 v[168:169], v[100:101], v[158:159] op_sel_hi:[1,0]
	v_pk_mul_f32 v[158:159], v[98:99], v[158:159] op_sel_hi:[1,0]
	v_cvt_pk_bf16_f32 v98, v126, v127
	v_cvt_pk_bf16_f32 v99, v128, v129
	v_cvt_pk_bf16_f32 v100, v122, v123
	v_cvt_pk_bf16_f32 v101, v124, v125
	v_pk_mul_f32 v[124:125], v[78:79], v[166:167] op_sel_hi:[1,0]
	global_store_dwordx4 v[148:149], v[98:101], off
	v_cvt_pk_bf16_f32 v78, v106, v107
	v_cvt_pk_bf16_f32 v79, v108, v109
	v_pk_mul_f32 v[120:121], v[120:121], v[162:163] op_sel_hi:[1,0]
	v_pk_mul_f32 v[118:119], v[118:119], v[162:163] op_sel_hi:[1,0]
	v_pk_mul_f32 v[122:123], v[80:81], v[166:167] op_sel_hi:[1,0]
	v_cvt_pk_bf16_f32 v80, v158, v159
	v_cvt_pk_bf16_f32 v81, v168, v169
	global_store_dwordx4 v[148:149], v[78:81], off offset:256
	v_pk_mul_f32 v[116:117], v[116:117], v[162:163] op_sel_hi:[1,0]
	v_pk_mul_f32 v[114:115], v[114:115], v[162:163] op_sel_hi:[1,0]
	v_cvt_pk_bf16_f32 v78, v118, v119
	v_cvt_pk_bf16_f32 v79, v120, v121
	v_pk_mul_f32 v[92:93], v[92:93], v[162:163] op_sel_hi:[1,0]
	v_pk_mul_f32 v[90:91], v[90:91], v[162:163] op_sel_hi:[1,0]
	v_cvt_pk_bf16_f32 v80, v114, v115
	v_cvt_pk_bf16_f32 v81, v116, v117
	global_store_dwordx4 v[156:157], v[78:81], off
	v_pk_mul_f32 v[88:89], v[88:89], v[162:163] op_sel_hi:[1,0]
	v_pk_mul_f32 v[86:87], v[86:87], v[162:163] op_sel_hi:[1,0]
	v_cvt_pk_bf16_f32 v78, v90, v91
	v_cvt_pk_bf16_f32 v79, v92, v93
	v_pk_mul_f32 v[112:113], v[112:113], v[166:167] op_sel_hi:[1,0]
	v_pk_mul_f32 v[110:111], v[110:111], v[166:167] op_sel_hi:[1,0]
	v_cvt_pk_bf16_f32 v80, v86, v87
	v_cvt_pk_bf16_f32 v81, v88, v89
	global_store_dwordx4 v[156:157], v[78:81], off offset:256
	v_pk_mul_f32 v[104:105], v[104:105], v[166:167] op_sel_hi:[1,0]
	v_pk_mul_f32 v[102:103], v[102:103], v[166:167] op_sel_hi:[1,0]
	v_cvt_pk_bf16_f32 v78, v110, v111
	v_cvt_pk_bf16_f32 v79, v112, v113
	v_pk_mul_f32 v[84:85], v[84:85], v[166:167] op_sel_hi:[1,0]
	v_pk_mul_f32 v[82:83], v[82:83], v[166:167] op_sel_hi:[1,0]
	v_cvt_pk_bf16_f32 v80, v102, v103
	v_cvt_pk_bf16_f32 v81, v104, v105
	global_store_dwordx4 v[160:161], v[78:81], off
	v_pk_mul_f32 v[96:97], v[96:97], v[150:151] op_sel_hi:[1,0]
	v_pk_mul_f32 v[94:95], v[94:95], v[150:151] op_sel_hi:[1,0]
	v_cvt_pk_bf16_f32 v78, v82, v83
	v_cvt_pk_bf16_f32 v79, v84, v85
	v_cvt_pk_bf16_f32 v80, v124, v125
	v_cvt_pk_bf16_f32 v81, v122, v123
	global_store_dwordx4 v[160:161], v[78:81], off offset:256
	v_pk_mul_f32 v[72:73], v[72:73], v[150:151] op_sel_hi:[1,0]
	v_pk_mul_f32 v[70:71], v[70:71], v[150:151] op_sel_hi:[1,0]
	v_pk_mul_f32 v[78:79], v[76:77], v[150:151] op_sel_hi:[1,0]
	v_pk_mul_f32 v[76:77], v[74:75], v[150:151] op_sel_hi:[1,0]
	v_cvt_pk_bf16_f32 v74, v94, v95
	v_cvt_pk_bf16_f32 v75, v96, v97
	v_pk_mul_f32 v[62:63], v[62:63], v[172:173] op_sel_hi:[1,0]
	v_cvt_pk_bf16_f32 v76, v76, v77
	v_cvt_pk_bf16_f32 v77, v78, v79
	global_store_dwordx4 v[164:165], v[74:77], off
	v_pk_mul_f32 v[64:65], v[64:65], v[172:173] op_sel_hi:[1,0]
	v_pk_mul_f32 v[56:57], v[56:57], v[172:173] op_sel_hi:[1,0]
	v_pk_mul_f32 v[74:75], v[68:69], v[150:151] op_sel_hi:[1,0]
	v_pk_mul_f32 v[68:69], v[66:67], v[150:151] op_sel_hi:[1,0]
	v_cvt_pk_bf16_f32 v66, v70, v71
	v_cvt_pk_bf16_f32 v67, v72, v73
	v_pk_mul_f32 v[54:55], v[54:55], v[172:173] op_sel_hi:[1,0]
	v_cvt_pk_bf16_f32 v68, v68, v69
	v_cvt_pk_bf16_f32 v69, v74, v75
	global_store_dwordx4 v[164:165], v[66:69], off offset:256
	v_pk_mul_f32 v[50:51], v[50:51], v[174:175] op_sel_hi:[1,0]
	v_pk_mul_f32 v[40:41], v[40:41], v[174:175] op_sel_hi:[1,0]
	v_pk_mul_f32 v[68:69], v[60:61], v[172:173] op_sel_hi:[1,0]
	v_pk_mul_f32 v[60:61], v[58:59], v[172:173] op_sel_hi:[1,0]
	v_cvt_pk_bf16_f32 v58, v62, v63
	v_add_co_u32_e32 v62, vcc, s54, v148
	v_cvt_pk_bf16_f32 v59, v64, v65
	v_cvt_pk_bf16_f32 v60, v60, v61
	v_cvt_pk_bf16_f32 v61, v68, v69
	v_lshl_add_u64 v[66:67], v[148:149], 0, s[14:15]
	s_nop 0
	v_addc_co_u32_e32 v63, vcc, 0, v149, vcc
	global_store_dwordx4 v[62:63], v[58:61], off
	v_pk_mul_f32 v[38:39], v[38:39], v[174:175] op_sel_hi:[1,0]
	v_pk_mul_f32 v[34:35], v[34:35], v[152:153] op_sel_hi:[1,0]
	v_pk_mul_f32 v[58:59], v[48:49], v[172:173] op_sel_hi:[1,0]
	v_pk_mul_f32 v[48:49], v[46:47], v[172:173] op_sel_hi:[1,0]
	v_cvt_pk_bf16_f32 v46, v54, v55
	v_cvt_pk_bf16_f32 v47, v56, v57
	v_pk_mul_f32 v[24:25], v[24:25], v[152:153] op_sel_hi:[1,0]
	v_cvt_pk_bf16_f32 v48, v48, v49
	v_cvt_pk_bf16_f32 v49, v58, v59
	global_store_dwordx4 v[66:67], v[46:49], off offset:256
; __device__ __forceinline__ unsigned cvt_pk_bf16(float lo, float hi) { unsigned r; asm volatile("v_cvt_pk_bf16_f32 %0, %1, %2" : "=v"(r) : "v"(lo), "v"(hi)); return r; }
;     __device__ __forceinline__ void operator()(const f32x4 (&acc)[2][2][4][2], const Unit& u, int wr, int wc, int fr, int fq) const {
;     ...
;             for (int m = 0; m < 4; ++m) { const int row = row0 + ai * HALF + m * 16; const float sc = scv[ai][m]; bf16_t* rowp = O + (size_t)row * ldc + col0;
; #pragma unroll
;                 for (int bj = 0; bj < 2; ++bj) { const f32x4 v0 = acc[ai][bj][m][0] * sc, v1 = acc[ai][bj][m][1] * sc;
;                     u32x4 w; w.x = cvt_pk_bf16(v0[0], v0[1]); w.y = cvt_pk_bf16(v0[2], v0[3]); w.z = cvt_pk_bf16(v1[0], v1[1]); w.w = cvt_pk_bf16(v1[2], v1[3]);
;                     *(u32x4*)(rowp + bj * HALF) = w; } }
	v_pk_mul_f32 v[22:23], v[22:23], v[152:153] op_sel_hi:[1,0]
	v_pk_mul_f32 v[18:19], v[18:19], v[146:147] op_sel_hi:[1,0]
	v_pk_mul_f32 v[48:49], v[52:53], v[174:175] op_sel_hi:[1,0]
	v_pk_mul_f32 v[52:53], v[44:45], v[174:175] op_sel_hi:[1,0]
	v_pk_mul_f32 v[44:45], v[42:43], v[174:175] op_sel_hi:[1,0]
	v_cvt_pk_bf16_f32 v42, v50, v51
	v_cvt_pk_bf16_f32 v43, v48, v49
	v_add_co_u32_e32 v48, vcc, s55, v148
	v_cvt_pk_bf16_f32 v44, v44, v45
	v_cvt_pk_bf16_f32 v45, v52, v53
	v_lshl_add_u64 v[46:47], v[148:149], 0, s[16:17]
	s_nop 0
	v_addc_co_u32_e32 v49, vcc, 0, v149, vcc
	global_store_dwordx4 v[48:49], v[42:45], off
	v_pk_mul_f32 v[8:9], v[8:9], v[146:147] op_sel_hi:[1,0]
	v_pk_mul_f32 v[6:7], v[6:7], v[146:147] op_sel_hi:[1,0]
	v_pk_mul_f32 v[42:43], v[32:33], v[174:175] op_sel_hi:[1,0]
	v_pk_mul_f32 v[32:33], v[30:31], v[174:175] op_sel_hi:[1,0]
	v_cvt_pk_bf16_f32 v30, v38, v39
	v_cvt_pk_bf16_f32 v31, v40, v41
	s_nop 0
	v_cvt_pk_bf16_f32 v32, v32, v33
	v_cvt_pk_bf16_f32 v33, v42, v43
	global_store_dwordx4 v[46:47], v[30:33], off offset:256
	s_nop 1
	v_pk_mul_f32 v[32:33], v[36:37], v[152:153] op_sel_hi:[1,0]
	v_pk_mul_f32 v[36:37], v[28:29], v[152:153] op_sel_hi:[1,0]
	v_pk_mul_f32 v[28:29], v[26:27], v[152:153] op_sel_hi:[1,0]
	v_cvt_pk_bf16_f32 v26, v34, v35
	v_cvt_pk_bf16_f32 v27, v32, v33
	v_add_co_u32_e32 v32, vcc, s56, v148
	v_cvt_pk_bf16_f32 v28, v28, v29
	v_cvt_pk_bf16_f32 v29, v36, v37
	v_lshl_add_u64 v[30:31], v[148:149], 0, s[18:19]
	s_nop 0
	v_addc_co_u32_e32 v33, vcc, 0, v149, vcc
	global_store_dwordx4 v[32:33], v[26:29], off
	s_nop 1
	v_pk_mul_f32 v[26:27], v[16:17], v[152:153] op_sel_hi:[1,0]
	v_pk_mul_f32 v[16:17], v[14:15], v[152:153] op_sel_hi:[1,0]
	v_cvt_pk_bf16_f32 v14, v22, v23
	v_cvt_pk_bf16_f32 v15, v24, v25
	s_nop 0
	v_cvt_pk_bf16_f32 v16, v16, v17
	v_cvt_pk_bf16_f32 v17, v26, v27
	global_store_dwordx4 v[30:31], v[14:17], off offset:256
	s_nop 1
	v_pk_mul_f32 v[16:17], v[20:21], v[146:147] op_sel_hi:[1,0]
	v_pk_mul_f32 v[20:21], v[12:13], v[146:147] op_sel_hi:[1,0]
	v_pk_mul_f32 v[12:13], v[10:11], v[146:147] op_sel_hi:[1,0]
	v_cvt_pk_bf16_f32 v10, v18, v19
	v_cvt_pk_bf16_f32 v11, v16, v17
	v_add_co_u32_e32 v16, vcc, s57, v148
	v_lshl_add_u64 v[14:15], v[148:149], 0, s[20:21]
	s_nop 0
	v_addc_co_u32_e32 v17, vcc, 0, v149, vcc
	v_cvt_pk_bf16_f32 v12, v12, v13
	v_cvt_pk_bf16_f32 v13, v20, v21
	global_store_dwordx4 v[16:17], v[10:13], off
	s_andn2_b64 vcc, exec, s[2:3]
	s_mov_b64 s[2:3], -1
	v_pk_mul_f32 v[10:11], v[4:5], v[146:147] op_sel_hi:[1,0]
	v_pk_mul_f32 v[4:5], v[2:3], v[146:147] op_sel_hi:[1,0]
	v_cvt_pk_bf16_f32 v2, v6, v7
	v_cvt_pk_bf16_f32 v3, v8, v9
	s_nop 0
	v_cvt_pk_bf16_f32 v4, v4, v5
	v_cvt_pk_bf16_f32 v5, v10, v11
	global_store_dwordx4 v[14:15], v[2:5], off offset:256
	s_waitcnt vmcnt(16)
	s_bfe_u32 s101, s82, 0x20000
	s_cmp_eq_u32 s101, 0
	s_cbranch_scc1 .Lcve_0
	s_cmp_eq_u32 s101, 2
	s_cbranch_scc1 .Lcvz_0
	v_mul_f32_e32 v176, v222, v176
	v_mul_f32_e32 v177, v222, v177
	v_mul_f32_e32 v178, v223, v178
	v_mul_f32_e32 v179, v223, v179
	v_mul_f32_e32 v180, v224, v180
	v_mul_f32_e32 v181, v224, v181
	v_mul_f32_e32 v182, v225, v182
	v_mul_f32_e32 v183, v225, v183
	v_mul_f32_e32 v184, v226, v184
	v_mul_f32_e32 v185, v226, v185
	v_mul_f32_e32 v186, v227, v186
	v_mul_f32_e32 v187, v227, v187
	v_mul_f32_e32 v188, v228, v188
	v_mul_f32_e32 v189, v228, v189
	v_mul_f32_e32 v190, v229, v190
	v_mul_f32_e32 v191, v229, v191
	v_cvt_pk_bf16_f32 v246, v176, v178
	v_cvt_pk_bf16_f32 v247, v180, v182
	v_cvt_pk_bf16_f32 v248, v184, v186
	v_cvt_pk_bf16_f32 v249, v188, v190
	global_store_dwordx4 v213, v[246:249], s[92:93]
	v_cvt_pk_bf16_f32 v250, v177, v179
	v_cvt_pk_bf16_f32 v251, v181, v183
	v_cvt_pk_bf16_f32 v252, v185, v187
	v_cvt_pk_bf16_f32 v253, v189, v191
	global_store_dwordx4 v218, v[250:253], s[92:93]
	s_branch .Lcve_0
.Lcvz_0:
	v_mov_b32_e32 v246, 0
	v_mov_b32_e32 v247, 0
	v_mov_b32_e32 v248, 0
	v_mov_b32_e32 v249, 0
	global_store_dwordx4 v213, v[246:249], s[92:93]
	global_store_dwordx4 v218, v[246:249], s[92:93]
	s_nop 1
.Lcve_0:
	s_bfe_u32 s101, s82, 0x20002
	s_cmp_eq_u32 s101, 0
	s_cbranch_scc1 .Lcve_1
	s_cmp_eq_u32 s101, 2
	s_cbranch_scc1 .Lcvz_1
	v_mul_f32_e32 v192, v222, v192
	v_mul_f32_e32 v193, v222, v193
	v_mul_f32_e32 v194, v223, v194
	v_mul_f32_e32 v195, v223, v195
	v_mul_f32_e32 v196, v224, v196
	v_mul_f32_e32 v197, v224, v197
	v_mul_f32_e32 v198, v225, v198
	v_mul_f32_e32 v199, v225, v199
	v_mul_f32_e32 v200, v226, v200
	v_mul_f32_e32 v201, v226, v201
	v_mul_f32_e32 v202, v227, v202
	v_mul_f32_e32 v203, v227, v203
	v_mul_f32_e32 v204, v228, v204
	v_mul_f32_e32 v205, v228, v205
	v_mul_f32_e32 v206, v229, v206
	v_mul_f32_e32 v207, v229, v207
	v_cvt_pk_bf16_f32 v246, v192, v194
	v_cvt_pk_bf16_f32 v247, v196, v198
	v_cvt_pk_bf16_f32 v248, v200, v202
	v_cvt_pk_bf16_f32 v249, v204, v206
	global_store_dwordx4 v213, v[246:249], s[94:95]
	v_cvt_pk_bf16_f32 v250, v193, v195
	v_cvt_pk_bf16_f32 v251, v197, v199
	v_cvt_pk_bf16_f32 v252, v201, v203
	v_cvt_pk_bf16_f32 v253, v205, v207
	global_store_dwordx4 v218, v[250:253], s[94:95]
	s_branch .Lcve_1
.Lcvz_1:
	v_mov_b32_e32 v246, 0
	v_mov_b32_e32 v247, 0
	v_mov_b32_e32 v248, 0
	v_mov_b32_e32 v249, 0
	global_store_dwordx4 v213, v[246:249], s[94:95]
	global_store_dwordx4 v218, v[246:249], s[94:95]
	s_nop 1
.Lcve_1:
	s_bfe_u32 s101, s82, 0x20004
	s_cmp_eq_u32 s101, 0
	s_cbranch_scc1 .Lcve_2
	s_cmp_eq_u32 s101, 2
	s_cbranch_scc1 .Lcvz_2
	v_mul_f32_e32 v230, v222, v230
	v_mul_f32_e32 v231, v222, v231
	v_mul_f32_e32 v232, v223, v232
	v_mul_f32_e32 v233, v223, v233
	v_mul_f32_e32 v234, v224, v234
	v_mul_f32_e32 v235, v224, v235
	v_mul_f32_e32 v236, v225, v236
	v_mul_f32_e32 v237, v225, v237
	v_mul_f32_e32 v238, v226, v238
	v_mul_f32_e32 v239, v226, v239
	v_mul_f32_e32 v240, v227, v240
	v_mul_f32_e32 v241, v227, v241
	v_mul_f32_e32 v242, v228, v242
	v_mul_f32_e32 v243, v228, v243
	v_mul_f32_e32 v244, v229, v244
	v_mul_f32_e32 v245, v229, v245
	v_cvt_pk_bf16_f32 v246, v230, v232
	v_cvt_pk_bf16_f32 v247, v234, v236
	v_cvt_pk_bf16_f32 v248, v238, v240
	v_cvt_pk_bf16_f32 v249, v242, v244
	global_store_dwordx4 v213, v[246:249], s[96:97]
	v_cvt_pk_bf16_f32 v250, v231, v233
	v_cvt_pk_bf16_f32 v251, v235, v237
	v_cvt_pk_bf16_f32 v252, v239, v241
	v_cvt_pk_bf16_f32 v253, v243, v245
	global_store_dwordx4 v218, v[250:253], s[96:97]
	s_branch .Lcve_2
.Lcvz_2:
	v_mov_b32_e32 v246, 0
	v_mov_b32_e32 v247, 0
	v_mov_b32_e32 v248, 0
	v_mov_b32_e32 v249, 0
	global_store_dwordx4 v213, v[246:249], s[96:97]
	global_store_dwordx4 v218, v[246:249], s[96:97]
	s_nop 1
.Lcve_2:
	s_add_i32 s98, s98, 1
	s_cbranch_vccnz .LBB0_1498
	s_andn2_b64 vcc, exec, s[4:5]
	s_cbranch_vccnz .LBB0_1497
	s_barrier
	s_branch .LBB0_1497

; __device__ __forceinline__ unsigned xb_add(unsigned* p, unsigned v) { return __hip_atomic_fetch_add(p, v, __ATOMIC_RELAXED, __HIP_MEMORY_SCOPE_AGENT); }
; __device__ __forceinline__ void p0_deferred(Frame& F, int my, int nconv, int part = -1) {
;     ...
;     if (part < 0 || part == 1) p0_transpose_matrix(F, FIN(F, 3) + (size_t)DM * 11360, DM, 11360, (bf16*)FW(F, WS_W_NSA_IN) + (size_t)NSA_NP * DM, NSA_NP / 32,
;         [](int nb) { const int n = nb * 32; return n < 7168 ? n : (n < 11264 ? n + 96 : (n < 11360 ? n - 4096 : -1)); }, it0, FIN(F, 1) + 3 * DM);
; __global__ void __launch_bounds__(NTHREADS, 2) fwd_kernel(Args args) {
;     ...
;                 if (F.tid == 0) { __builtin_amdgcn_fence(__ATOMIC_RELEASE, "agent"); asm volatile("s_waitcnt vmcnt(0)" ::: "memory"); (void)xb_add(ctl + CW_WOF, 1u); }
;                 p0_deferred(F, j, 128, 1);
.LBB0_1691:
	s_or_b64 exec, exec, s[4:5]
	s_branch .LBB0_1709
	v_readlane_b32 s6, v254, 7
	v_readlane_b32 s7, v254, 8
	s_load_dwordx2 s[4:5], s[6:7], 0x8
	s_nop 0
	s_load_dwordx2 s[6:7], s[6:7], 0x18
	v_lshlrev_b32_e32 v2, 2, v16
	v_mov_b32_e32 v3, 0
	v_mov_b32_e32 v15, v3
	s_waitcnt lgkmcnt(0)
	v_lshl_add_u64 v[4:5], s[4:5], 0, v[2:3]
	s_mov_b64 s[4:5], 0xc000
	v_lshlrev_b32_e32 v2, 1, v16
	v_lshl_add_u64 v[18:19], v[4:5], 0, s[4:5]
	v_lshl_add_u64 v[4:5], s[70:71], 0, v[2:3]
	s_mov_b64 s[4:5], 0x5c00000
	v_lshl_add_u64 v[20:21], v[4:5], 0, s[4:5]
	v_lshl_add_u64 v[4:5], s[6:7], 0, v[14:15]
	s_mov_b64 s[4:5], 0xb180000
	v_lshl_add_u64 v[22:23], v[4:5], 0, s[4:5]
	s_mov_b32 s11, 0xb180
	v_add_u32_e32 v32, 0x400, v30
	v_add_u32_e32 v33, 0x800, v30
	v_add_u32_e32 v36, 0xc00, v30
	v_add_u32_e32 v37, 0x1000, v30
	v_add_u32_e32 v38, 0x1400, v30
	v_add_u32_e32 v39, 0x1800, v30
	v_add_u32_e32 v40, 0x1c00, v30
	v_mov_b32_e32 v2, v3
	v_mov_b32_e32 v4, v3
	v_mov_b32_e32 v5, v3
	s_branch .LBB0_1693
